# MLA attention key-tile loop hand-pipelined: K/V LDS fragment reads issued up front with counted lgkmcnt, exp/cvt interleaved with PV MFMAs
# speedup vs baseline: 1.0101x; 1.0101x over previous
.LBB0_496:
	s_add_i32 s17, s15, 2
	s_add_i32 s15, s15, 1
	s_bitcmp1_b32 s15, 0
	s_cselect_b32 s18, 0x6400, 0
	v_add_u32_e32 v126, s18, v123
	v_add_u32_e32 v234, s18, v118
	ds_read_b128 v[148:151], v126
	ds_read_b128 v[152:155], v126 offset:6656
	ds_read_b128 v[156:159], v126 offset:32
	ds_read_b128 v[160:163], v126 offset:6688
	ds_read_b128 v[164:167], v126 offset:64
	ds_read_b128 v[168:171], v126 offset:6720
	ds_read_b128 v[172:175], v126 offset:96
	ds_read_b128 v[176:179], v126 offset:6752
	ds_read_b128 v[180:183], v126 offset:128
	ds_read_b128 v[184:187], v126 offset:6784
	ds_read_b128 v[188:191], v126 offset:160
	ds_read_b128 v[192:195], v126 offset:6816
	v_mov_b64_e32 v[50:51], v[98:99]
	v_mov_b64_e32 v[52:53], v[100:101]
	v_mfma_f32_32x32x16_bf16 v[34:49], v[90:93], v[98:101], 0
	s_cmp_lt_u32 s17, s5
	s_cselect_b32 s10, 0, s5
	s_cselect_b32 s11, s59, s14
	s_lshl_b32 s10, s10, 6
	s_sub_i32 s18, s11, s10
	v_mfma_f32_32x32x16_bf16 v[50:65], v[90:93], v[50:53], 0
	v_add_u32_e32 v236, s18, v125
	v_ashrrev_i32_e32 v237, 31, v236
	v_lshlrev_b64 v[236:237], 10, v[236:237]
	v_lshl_add_u64 v[236:237], v[114:115], 0, v[236:237]
	global_load_dwordx4 v[106:109], v[236:237], off
	global_load_dwordx4 v[102:105], v[236:237], off offset:128
	s_and_saveexec_b64 s[10:11], s[38:39]
	s_cbranch_execz .LBB0_498
	v_add_u32_e32 v236, s18, v124
	v_ashrrev_i32_e32 v237, 31, v236
	v_lshlrev_b64 v[236:237], 6, v[236:237]
	v_lshl_add_u64 v[236:237], v[116:117], 0, v[236:237]
	global_load_dwordx4 v[94:97], v[236:237], off
.LBB0_498:
	s_or_b64 exec, exec, s[10:11]
	s_nop 0
	s_waitcnt lgkmcnt(11)
	v_mfma_f32_32x32x16_bf16 v[34:49], v[148:151], v[74:77], v[34:49]
	s_waitcnt lgkmcnt(10)
	v_mfma_f32_32x32x16_bf16 v[50:65], v[152:155], v[74:77], v[50:65]
	s_waitcnt lgkmcnt(9)
	v_mfma_f32_32x32x16_bf16 v[34:49], v[156:159], v[66:69], v[34:49]
	s_waitcnt lgkmcnt(8)
	v_mfma_f32_32x32x16_bf16 v[50:65], v[160:163], v[66:69], v[50:65]
	s_waitcnt lgkmcnt(7)
	v_mfma_f32_32x32x16_bf16 v[34:49], v[164:167], v[82:85], v[34:49]
	s_waitcnt lgkmcnt(6)
	v_mfma_f32_32x32x16_bf16 v[50:65], v[168:171], v[82:85], v[50:65]
	s_waitcnt lgkmcnt(5)
	v_mfma_f32_32x32x16_bf16 v[34:49], v[172:175], v[70:73], v[34:49]
	s_waitcnt lgkmcnt(4)
	v_mfma_f32_32x32x16_bf16 v[50:65], v[176:179], v[70:73], v[50:65]
	s_waitcnt lgkmcnt(3)
	v_mfma_f32_32x32x16_bf16 v[34:49], v[180:183], v[86:89], v[34:49]
	s_waitcnt lgkmcnt(2)
	v_mfma_f32_32x32x16_bf16 v[50:65], v[184:187], v[86:89], v[50:65]
	s_waitcnt lgkmcnt(1)
	v_mfma_f32_32x32x16_bf16 v[34:49], v[188:191], v[78:81], v[34:49]
	s_waitcnt lgkmcnt(0)
	v_mfma_f32_32x32x16_bf16 v[50:65], v[192:195], v[78:81], v[50:65]
	ds_read_b64_tr_b16 v[196:197], v234 offset:13312
	ds_read_b64_tr_b16 v[198:199], v234 offset:14848
	ds_read_b64_tr_b16 v[200:201], v234 offset:16384
	ds_read_b64_tr_b16 v[202:203], v234 offset:17920
	ds_read_b64_tr_b16 v[204:205], v234 offset:19456
	ds_read_b64_tr_b16 v[206:207], v234 offset:20992
	ds_read_b64_tr_b16 v[214:215], v234 offset:22528
	ds_read_b64_tr_b16 v[216:217], v234 offset:24064
	s_nop 4
	v_max_f32_e32 v126, v35, v35
	v_max_f32_e32 v132, v34, v34
	v_max_f32_e32 v126, v132, v126
	v_max3_f32 v128, v36, v37, v51
	v_max3_f32 v126, v126, v50, v52
	v_max3_f32 v126, v126, v53, v38
	v_max3_f32 v128, v128, v40, v41
	v_max3_f32 v126, v126, v39, v54
	v_max3_f32 v128, v128, v56, v57
	v_max3_f32 v126, v126, v55, v42
	v_max3_f32 v128, v128, v44, v45
	v_max3_f32 v126, v126, v43, v58
	v_max3_f32 v128, v128, v60, v61
	v_max3_f32 v126, v126, v59, v46
	v_max3_f32 v128, v128, v48, v49
	v_max3_f32 v126, v126, v47, v62
	v_max3_f32 v128, v128, v64, v65
	v_max3_f32 v126, v126, v63, v128
	ds_bpermute_b32 v128, v113, v126
	s_waitcnt lgkmcnt(0)
	ds_read_b64_tr_b16 v[218:219], v234 offset:13376
	ds_read_b64_tr_b16 v[220:221], v234 offset:14912
	ds_read_b64_tr_b16 v[222:223], v234 offset:16448
	ds_read_b64_tr_b16 v[224:225], v234 offset:17984
	ds_read_b64_tr_b16 v[226:227], v234 offset:19520
	ds_read_b64_tr_b16 v[228:229], v234 offset:21056
	ds_read_b64_tr_b16 v[230:231], v234 offset:22592
	ds_read_b64_tr_b16 v[232:233], v234 offset:24128
	v_max_f32_e32 v128, v128, v128
	v_max_f32_e32 v126, v126, v128
	v_cmp_lt_f32_e32 vcc, s7, v126
	s_cbranch_vccz .LBB0_502
	v_max_f32_e32 v126, v126, v126
	v_max_f32_e32 v126, 0, v126
	v_add_f32_e32 v126, v127, v126
	v_cvt_pk_bf16_f32 v126, v126, v1
	s_nop 0
	v_lshlrev_b32_e32 v126, 16, v126
	s_and_saveexec_b64 s[10:11], s[36:37]
	s_cbranch_execz .LBB0_501
	v_xor_b32_e32 v128, 0x80000000, v126
	v_cvt_pk_bf16_f32 v128, v128, v1
	s_nop 0
	v_bfi_b32 v98, s2, v128, v98

.LBB0_503:
	v_exp_f32_e32 v34, v34
	v_exp_f32_e32 v35, v35
	v_exp_f32_e32 v36, v36
	v_exp_f32_e32 v37, v37
	v_exp_f32_e32 v38, v38
	v_exp_f32_e32 v39, v39
	v_exp_f32_e32 v40, v40
	v_exp_f32_e32 v41, v41
	v_cvt_pk_bf16_f32 v128, v34, v35
	v_cvt_pk_bf16_f32 v129, v36, v37
	v_cvt_pk_bf16_f32 v130, v38, v39
	v_cvt_pk_bf16_f32 v131, v40, v41
	v_exp_f32_e32 v42, v42
	v_exp_f32_e32 v43, v43
	v_mfma_f32_32x32x16_bf16 v[2:17], v[196:199], v[128:131], v[2:17]
	s_waitcnt lgkmcnt(6)
	v_mfma_f32_32x32x16_bf16 v[18:33], v[218:221], v[128:131], v[18:33]
	v_exp_f32_e32 v44, v44
	v_exp_f32_e32 v45, v45
	v_exp_f32_e32 v46, v46
	v_exp_f32_e32 v47, v47
	v_exp_f32_e32 v48, v48
	v_exp_f32_e32 v49, v49
	v_cvt_pk_bf16_f32 v136, v42, v43
	v_cvt_pk_bf16_f32 v137, v44, v45
	v_cvt_pk_bf16_f32 v138, v46, v47
	v_cvt_pk_bf16_f32 v139, v48, v49
	v_exp_f32_e32 v50, v50
	v_exp_f32_e32 v51, v51
	v_mfma_f32_32x32x16_bf16 v[2:17], v[200:203], v[136:139], v[2:17]
	s_waitcnt lgkmcnt(4)
	v_mfma_f32_32x32x16_bf16 v[18:33], v[222:225], v[136:139], v[18:33]
	v_exp_f32_e32 v52, v52
	v_exp_f32_e32 v53, v53
	v_exp_f32_e32 v54, v54
	v_exp_f32_e32 v55, v55
	v_exp_f32_e32 v56, v56
	v_exp_f32_e32 v57, v57
	v_cvt_pk_bf16_f32 v132, v50, v51
	v_cvt_pk_bf16_f32 v133, v52, v53
	v_cvt_pk_bf16_f32 v134, v54, v55
	v_cvt_pk_bf16_f32 v135, v56, v57
	v_exp_f32_e32 v58, v58
	v_exp_f32_e32 v59, v59
	v_mfma_f32_32x32x16_bf16 v[2:17], v[204:207], v[132:135], v[2:17]
	s_waitcnt lgkmcnt(2)
	v_mfma_f32_32x32x16_bf16 v[18:33], v[226:229], v[132:135], v[18:33]
	v_exp_f32_e32 v60, v60
	v_exp_f32_e32 v61, v61
	v_exp_f32_e32 v62, v62
	v_exp_f32_e32 v63, v63
	v_exp_f32_e32 v64, v64
	v_exp_f32_e32 v65, v65
	v_cvt_pk_bf16_f32 v140, v58, v59
	v_cvt_pk_bf16_f32 v141, v60, v61
	v_cvt_pk_bf16_f32 v142, v62, v63
	v_cvt_pk_bf16_f32 v143, v64, v65
	s_bitcmp1_b32 s17, 0
	s_cselect_b32 s10, 0x6400, 0
	s_add_i32 s17, s10, 0
	v_mfma_f32_32x32x16_bf16 v[2:17], v[214:217], v[140:143], v[2:17]
	s_waitcnt lgkmcnt(0)
	v_mfma_f32_32x32x16_bf16 v[18:33], v[230:233], v[140:143], v[18:33]
	v_add_u32_e32 v238, s17, v120
	v_add_u32_e32 v239, s17, v121
	s_waitcnt vmcnt(1)
	ds_write_b128 v238, v[106:109]
	s_waitcnt vmcnt(0)
	ds_write_b128 v239, v[102:105] offset:13312
	s_and_saveexec_b64 s[10:11], s[38:39]
	v_add3_u32 v238, s17, v112, v122
	ds_write_b128 v238, v[94:97] offset:128
	s_or_b64 exec, exec, s[10:11]
	v_add_f32_e32 v34, v50, v34
	v_add_f32_e32 v35, v51, v35
	v_add_f32_e32 v34, 0, v34
	v_add_f32_e32 v36, v52, v36
	v_add_f32_e32 v34, v35, v34
	v_add_f32_e32 v37, v53, v37
	v_add_f32_e32 v34, v36, v34
	v_add_f32_e32 v38, v54, v38
	v_add_f32_e32 v34, v37, v34
	v_add_f32_e32 v39, v55, v39
	v_add_f32_e32 v34, v38, v34
	v_add_f32_e32 v40, v56, v40
	v_add_f32_e32 v34, v39, v34
	v_add_f32_e32 v41, v57, v41
	v_add_f32_e32 v34, v40, v34
	v_add_f32_e32 v42, v58, v42
	v_add_f32_e32 v34, v41, v34
	v_add_f32_e32 v43, v59, v43
	v_add_f32_e32 v34, v42, v34
	v_add_f32_e32 v44, v60, v44
	v_add_f32_e32 v34, v43, v34
	v_add_f32_e32 v45, v61, v45
	v_add_f32_e32 v34, v44, v34
	v_add_f32_e32 v46, v62, v46
	v_add_f32_e32 v34, v45, v34
	v_add_f32_e32 v47, v63, v47
	v_add_f32_e32 v34, v46, v34
	v_add_f32_e32 v48, v64, v48
	v_add_f32_e32 v34, v47, v34
	v_add_f32_e32 v49, v65, v49
	v_add_f32_e32 v34, v48, v34
	v_add_f32_e32 v34, v49, v34
	v_add_f32_e32 v119, v119, v34
	v_add_u32_e32 v124, 64, v124
	s_cmp_lg_u32 s16, s15
	v_add_u32_e32 v125, 64, v125
	s_waitcnt lgkmcnt(0)
	s_barrier
	s_cbranch_scc0 .LBB0_507
	v_mov_b32_e32 v127, v126
	s_branch .LBB0_496
